# v39: weight conversion group 3 split (ff2_in items in P2 on workgroups without a split-K tail unit, rest in P4 on workgroups without a 4th-round half unit), two items in flight, P4 last round as half
# baseline (speedup 1.0000x reference)
.LBB0_232:
	v_readlane_b32 s36, v255, 40
	s_cmp_lt_i32 s91, 4
	v_readlane_b32 s40, v255, 44
	v_readlane_b32 s41, v255, 45
	v_readlane_b32 s42, v255, 46
	v_readlane_b32 s43, v255, 47
	v_readlane_b32 s46, v255, 50
	v_readlane_b32 s47, v255, 51
	v_readlane_b32 s37, v255, 41
	v_readlane_b32 s38, v255, 42
	v_readlane_b32 s39, v255, 43
	v_readlane_b32 s44, v255, 48
	v_readlane_b32 s45, v255, 49
	v_readlane_b32 s48, v255, 52
	v_readlane_b32 s49, v255, 53
	v_readlane_b32 s50, v255, 54
	v_readlane_b32 s51, v255, 55
	s_cbranch_scc1 .LBB0_286
	s_cmpk_lt_u32 s24, 88
	s_cbranch_scc1 .Lcvp2_end
	s_sub_i32 s1, s24, 88
	s_lshl_b32 s1, s1, 3
	s_add_i32 s6, s1, s83
	s_movk_i32 s0, 88
	s_cmpk_gt_u32 s6, 2815
	s_cbranch_scc1 .Lcvp2_end
	s_sub_i32 s7, s33, s0
	s_lshl_b32 s7, s7, 3
	v_mbcnt_lo_u32_b32 v1, -1, 0
	v_mbcnt_hi_u32_b32 v1, -1, v1
	v_and_b32_e32 v2, 31, v1
	v_lshrrev_b32_e32 v3, 5, v1
	s_mul_i32 s4, s83, 0x4400
	v_mad_u32_u24 v4, v3, 33, v2
	v_lshl_add_u32 v4, v4, 2, s4
	v_and_b32_e32 v5, 7, v1
	v_lshrrev_b32_e32 v6, 3, v1
	v_mul_u32_u24_e32 v7, 0x108, v5
	v_add_u32_e32 v7, v7, v6
	v_lshl_add_u32 v7, v7, 2, s4
.Lcvp2_item:
	s_add_i32 s23, s6, s7
	s_cmpk_lt_u32 s23, 2816
	s_cbranch_scc0 .Lcvp2_single
	s_cmpk_lt_u32 s6, 2816
	s_cbranch_scc0 .Lcvp2_fo_a
	s_mul_i32 s1, s6, 5958
	s_lshr_b32 s1, s1, 20
	s_mul_i32 s2, s1, 176
	s_sub_i32 s2, s6, s2
	s_lshl_b32 s18, s2, 5
	s_lshl_b32 s17, s1, 6
	s_cmpk_lt_u32 s18, 2816
	s_cselect_b32 s2, 0, 2816
	s_cselect_b32 s3, 0, 128
	s_sub_i32 s2, s18, s2
	s_lshr_b32 s16, s2, 7
	s_lshl_b32 s16, s16, 8
	s_and_b32 s2, s2, 127
	s_add_i32 s16, s16, s2
	s_add_i32 s16, s16, s3
	s_mov_b64 s[10:11], s[40:41]
	s_movk_i32 s12, 5632
	s_movk_i32 s13, 1024
	s_add_u32 s14, s26, 0x1400000
	s_addc_u32 s15, s27, 0
	s_branch .Lcvp2_go_a

.Lcvp2_go_b:
	s_mul_i32 s1, s17, s12
	s_add_i32 s1, s1, s18
	s_lshl_b32 s1, s1, 2
	s_add_u32 s10, s10, s1
	s_addc_u32 s11, s11, 0
	v_mul_lo_u32 v8, v3, s12
	v_add_lshl_u32 v8, v8, v2, 2
	s_lshl_b32 s19, s12, 3
	global_load_dword v48, v8, s[10:11] nt
	s_add_u32 s10, s10, s19
	s_addc_u32 s11, s11, 0
	global_load_dword v49, v8, s[10:11] nt
	s_add_u32 s10, s10, s19
	s_addc_u32 s11, s11, 0
	global_load_dword v50, v8, s[10:11] nt
	s_add_u32 s10, s10, s19
	s_addc_u32 s11, s11, 0
	global_load_dword v51, v8, s[10:11] nt
	s_add_u32 s10, s10, s19
	s_addc_u32 s11, s11, 0
	global_load_dword v52, v8, s[10:11] nt
	s_add_u32 s10, s10, s19
	s_addc_u32 s11, s11, 0
	global_load_dword v53, v8, s[10:11] nt
	s_add_u32 s10, s10, s19
	s_addc_u32 s11, s11, 0
	global_load_dword v54, v8, s[10:11] nt
	s_add_u32 s10, s10, s19
	s_addc_u32 s11, s11, 0
	global_load_dword v55, v8, s[10:11] nt
	s_add_u32 s10, s10, s19
	s_addc_u32 s11, s11, 0
	global_load_dword v56, v8, s[10:11] nt
	s_add_u32 s10, s10, s19
	s_addc_u32 s11, s11, 0
	global_load_dword v57, v8, s[10:11] nt
	s_add_u32 s10, s10, s19
	s_addc_u32 s11, s11, 0
	global_load_dword v58, v8, s[10:11] nt
	s_add_u32 s10, s10, s19
	s_addc_u32 s11, s11, 0
	global_load_dword v59, v8, s[10:11] nt
	s_add_u32 s10, s10, s19
	s_addc_u32 s11, s11, 0
	global_load_dword v60, v8, s[10:11] nt
	s_add_u32 s10, s10, s19
	s_addc_u32 s11, s11, 0
	global_load_dword v61, v8, s[10:11] nt
	s_add_u32 s10, s10, s19
	s_addc_u32 s11, s11, 0
	global_load_dword v62, v8, s[10:11] nt
	s_add_u32 s10, s10, s19
	s_addc_u32 s11, s11, 0
	global_load_dword v63, v8, s[10:11] nt
	s_add_u32 s10, s10, s19
	s_addc_u32 s11, s11, 0
	global_load_dword v64, v8, s[10:11] nt
	s_add_u32 s10, s10, s19
	s_addc_u32 s11, s11, 0
	global_load_dword v65, v8, s[10:11] nt
	s_add_u32 s10, s10, s19
	s_addc_u32 s11, s11, 0
	global_load_dword v66, v8, s[10:11] nt
	s_add_u32 s10, s10, s19
	s_addc_u32 s11, s11, 0
	global_load_dword v67, v8, s[10:11] nt
	s_add_u32 s10, s10, s19
	s_addc_u32 s11, s11, 0
	global_load_dword v68, v8, s[10:11] nt
	s_add_u32 s10, s10, s19
	s_addc_u32 s11, s11, 0
	global_load_dword v69, v8, s[10:11] nt
	s_add_u32 s10, s10, s19
	s_addc_u32 s11, s11, 0
	global_load_dword v70, v8, s[10:11] nt
	s_add_u32 s10, s10, s19
	s_addc_u32 s11, s11, 0
	global_load_dword v71, v8, s[10:11] nt
	s_add_u32 s10, s10, s19
	s_addc_u32 s11, s11, 0
	global_load_dword v72, v8, s[10:11] nt
	s_add_u32 s10, s10, s19
	s_addc_u32 s11, s11, 0
	global_load_dword v73, v8, s[10:11] nt
	s_add_u32 s10, s10, s19
	s_addc_u32 s11, s11, 0
	global_load_dword v74, v8, s[10:11] nt
	s_add_u32 s10, s10, s19
	s_addc_u32 s11, s11, 0
	global_load_dword v75, v8, s[10:11] nt
	s_add_u32 s10, s10, s19
	s_addc_u32 s11, s11, 0
	global_load_dword v76, v8, s[10:11] nt
	s_add_u32 s10, s10, s19
	s_addc_u32 s11, s11, 0
	global_load_dword v77, v8, s[10:11] nt
	s_add_u32 s10, s10, s19
	s_addc_u32 s11, s11, 0
	global_load_dword v78, v8, s[10:11] nt
	s_add_u32 s10, s10, s19
	s_addc_u32 s11, s11, 0
	global_load_dword v79, v8, s[10:11] nt
	s_mul_i32 s1, s16, s13
	s_add_i32 s1, s1, s17
	s_lshl_b32 s1, s1, 1
	s_add_u32 s14, s14, s1
	s_addc_u32 s15, s15, 0
	s_waitcnt vmcnt(63)
	ds_write_b32 v4, v16 offset:0
	s_waitcnt vmcnt(62)
	ds_write_b32 v4, v17 offset:264
	s_waitcnt vmcnt(61)
	ds_write_b32 v4, v18 offset:528
	s_waitcnt vmcnt(60)
	ds_write_b32 v4, v19 offset:792
	s_waitcnt vmcnt(59)
	ds_write_b32 v4, v20 offset:1056
	s_waitcnt vmcnt(58)
	ds_write_b32 v4, v21 offset:1320
	s_waitcnt vmcnt(57)
	ds_write_b32 v4, v22 offset:1584
	s_waitcnt vmcnt(56)
	ds_write_b32 v4, v23 offset:1848
	s_waitcnt vmcnt(55)
	ds_write_b32 v4, v24 offset:2112
	s_waitcnt vmcnt(54)
	ds_write_b32 v4, v25 offset:2376
	s_waitcnt vmcnt(53)
	ds_write_b32 v4, v26 offset:2640
	s_waitcnt vmcnt(52)
	ds_write_b32 v4, v27 offset:2904
	s_waitcnt vmcnt(51)
	ds_write_b32 v4, v28 offset:3168
	s_waitcnt vmcnt(50)
	ds_write_b32 v4, v29 offset:3432
	s_waitcnt vmcnt(49)
	ds_write_b32 v4, v30 offset:3696
	s_waitcnt vmcnt(48)
	ds_write_b32 v4, v31 offset:3960
	s_waitcnt vmcnt(47)
	ds_write_b32 v4, v32 offset:4224
	s_waitcnt vmcnt(46)
	ds_write_b32 v4, v33 offset:4488
	s_waitcnt vmcnt(45)
	ds_write_b32 v4, v34 offset:4752
	s_waitcnt vmcnt(44)
	ds_write_b32 v4, v35 offset:5016
	s_waitcnt vmcnt(43)
	ds_write_b32 v4, v36 offset:5280
	s_waitcnt vmcnt(42)
	ds_write_b32 v4, v37 offset:5544
	s_waitcnt vmcnt(41)
	ds_write_b32 v4, v38 offset:5808
	s_waitcnt vmcnt(40)
	ds_write_b32 v4, v39 offset:6072
	s_waitcnt vmcnt(39)
	ds_write_b32 v4, v40 offset:6336
	s_waitcnt vmcnt(38)
	ds_write_b32 v4, v41 offset:6600
	s_waitcnt vmcnt(37)
	ds_write_b32 v4, v42 offset:6864
	s_waitcnt vmcnt(36)
	ds_write_b32 v4, v43 offset:7128
	s_waitcnt vmcnt(35)
	ds_write_b32 v4, v44 offset:7392
	s_waitcnt vmcnt(34)
	ds_write_b32 v4, v45 offset:7656
	s_waitcnt vmcnt(33)
	ds_write_b32 v4, v46 offset:7920
	s_waitcnt vmcnt(32)
	ds_write_b32 v4, v47 offset:8184
	s_waitcnt vmcnt(31)
	ds_write_b32 v4, v48 offset:8448
	s_waitcnt vmcnt(30)
	ds_write_b32 v4, v49 offset:8712
	s_waitcnt vmcnt(29)
	ds_write_b32 v4, v50 offset:8976
	s_waitcnt vmcnt(28)
	ds_write_b32 v4, v51 offset:9240
	s_waitcnt vmcnt(27)
	ds_write_b32 v4, v52 offset:9504
	s_waitcnt vmcnt(26)
	ds_write_b32 v4, v53 offset:9768
	s_waitcnt vmcnt(25)
	ds_write_b32 v4, v54 offset:10032
	s_waitcnt vmcnt(24)
	ds_write_b32 v4, v55 offset:10296
	s_waitcnt vmcnt(23)
	ds_write_b32 v4, v56 offset:10560
	s_waitcnt vmcnt(22)
	ds_write_b32 v4, v57 offset:10824
	s_waitcnt vmcnt(21)
	ds_write_b32 v4, v58 offset:11088
	s_waitcnt vmcnt(20)
	ds_write_b32 v4, v59 offset:11352
	s_waitcnt vmcnt(19)
	ds_write_b32 v4, v60 offset:11616
	s_waitcnt vmcnt(18)
	ds_write_b32 v4, v61 offset:11880
	s_waitcnt vmcnt(17)
	ds_write_b32 v4, v62 offset:12144
	s_waitcnt vmcnt(16)
	ds_write_b32 v4, v63 offset:12408
	s_waitcnt vmcnt(15)
	ds_write_b32 v4, v64 offset:12672
	s_waitcnt vmcnt(14)
	ds_write_b32 v4, v65 offset:12936
	s_waitcnt vmcnt(13)
	ds_write_b32 v4, v66 offset:13200
	s_waitcnt vmcnt(12)
	ds_write_b32 v4, v67 offset:13464
	s_waitcnt vmcnt(11)
	ds_write_b32 v4, v68 offset:13728
	s_waitcnt vmcnt(10)
	ds_write_b32 v4, v69 offset:13992
	s_waitcnt vmcnt(9)
	ds_write_b32 v4, v70 offset:14256
	s_waitcnt vmcnt(8)
	ds_write_b32 v4, v71 offset:14520
	s_waitcnt vmcnt(7)
	ds_write_b32 v4, v72 offset:14784
	s_waitcnt vmcnt(6)
	ds_write_b32 v4, v73 offset:15048
	s_waitcnt vmcnt(5)
	ds_write_b32 v4, v74 offset:15312
	s_waitcnt vmcnt(4)
	ds_write_b32 v4, v75 offset:15576
	s_waitcnt vmcnt(3)
	ds_write_b32 v4, v76 offset:15840
	s_waitcnt vmcnt(2)
	ds_write_b32 v4, v77 offset:16104
	s_waitcnt vmcnt(1)
	ds_write_b32 v4, v78 offset:16368
	s_waitcnt vmcnt(0)
	ds_write_b32 v4, v79 offset:16632
	s_waitcnt lgkmcnt(0)
	v_mul_lo_u32 v9, v6, s22
	v_lshl_add_u32 v96, v5, 3, v9
	v_lshlrev_b32_e32 v9, 1, v96
	s_lshl_b32 s19, s22, 4
	ds_read_b32 v112, v7 offset:0
	ds_read_b32 v113, v7 offset:132
	ds_read_b32 v114, v7 offset:264
	ds_read_b32 v115, v7 offset:396
	ds_read_b32 v116, v7 offset:528
	ds_read_b32 v117, v7 offset:660
	ds_read_b32 v118, v7 offset:792
	ds_read_b32 v119, v7 offset:924
	s_waitcnt lgkmcnt(0)
	v_cvt_pk_bf16_f32 v96, v112, v113
	v_cvt_pk_bf16_f32 v97, v114, v115
	v_cvt_pk_bf16_f32 v98, v116, v117
	v_cvt_pk_bf16_f32 v99, v118, v119
	global_store_dwordx4 v9, v[96:99], s[20:21] nt
	s_add_u32 s20, s20, s19
	s_addc_u32 s21, s21, 0
	ds_read_b32 v120, v7 offset:32
	ds_read_b32 v121, v7 offset:164
	ds_read_b32 v122, v7 offset:296
	ds_read_b32 v123, v7 offset:428
	ds_read_b32 v124, v7 offset:560
	ds_read_b32 v125, v7 offset:692
	ds_read_b32 v126, v7 offset:824
	ds_read_b32 v127, v7 offset:956
	s_waitcnt lgkmcnt(0)
	v_cvt_pk_bf16_f32 v100, v120, v121
	v_cvt_pk_bf16_f32 v101, v122, v123
	v_cvt_pk_bf16_f32 v102, v124, v125
	v_cvt_pk_bf16_f32 v103, v126, v127
	global_store_dwordx4 v9, v[100:103], s[20:21] nt
	s_add_u32 s20, s20, s19
	s_addc_u32 s21, s21, 0
	ds_read_b32 v128, v7 offset:64
	ds_read_b32 v129, v7 offset:196
	ds_read_b32 v130, v7 offset:328
	ds_read_b32 v131, v7 offset:460
	ds_read_b32 v132, v7 offset:592
	ds_read_b32 v133, v7 offset:724
	ds_read_b32 v134, v7 offset:856
	ds_read_b32 v135, v7 offset:988
	s_waitcnt lgkmcnt(0)
	v_cvt_pk_bf16_f32 v104, v128, v129
	v_cvt_pk_bf16_f32 v105, v130, v131
	v_cvt_pk_bf16_f32 v106, v132, v133
	v_cvt_pk_bf16_f32 v107, v134, v135
	global_store_dwordx4 v9, v[104:107], s[20:21] nt
	s_add_u32 s20, s20, s19
	s_addc_u32 s21, s21, 0
	ds_read_b32 v136, v7 offset:96
	ds_read_b32 v137, v7 offset:228
	ds_read_b32 v138, v7 offset:360
	ds_read_b32 v139, v7 offset:492
	ds_read_b32 v140, v7 offset:624
	ds_read_b32 v141, v7 offset:756
	ds_read_b32 v142, v7 offset:888
	ds_read_b32 v143, v7 offset:1020
	s_waitcnt lgkmcnt(0)
	v_cvt_pk_bf16_f32 v108, v136, v137
	v_cvt_pk_bf16_f32 v109, v138, v139
	v_cvt_pk_bf16_f32 v110, v140, v141
	v_cvt_pk_bf16_f32 v111, v142, v143
	global_store_dwordx4 v9, v[108:111], s[20:21] nt
	v_mul_lo_u32 v9, v6, s13
	v_lshl_add_u32 v96, v5, 3, v9
	v_lshlrev_b32_e32 v9, 1, v96
	s_lshl_b32 s19, s13, 4
	ds_read_b32 v112, v7 offset:8448
	ds_read_b32 v113, v7 offset:8580
	ds_read_b32 v114, v7 offset:8712
	ds_read_b32 v115, v7 offset:8844
	ds_read_b32 v116, v7 offset:8976
	ds_read_b32 v117, v7 offset:9108
	ds_read_b32 v118, v7 offset:9240
	ds_read_b32 v119, v7 offset:9372
	s_waitcnt lgkmcnt(0)
	v_cvt_pk_bf16_f32 v96, v112, v113
	v_cvt_pk_bf16_f32 v97, v114, v115
	v_cvt_pk_bf16_f32 v98, v116, v117
	v_cvt_pk_bf16_f32 v99, v118, v119
	global_store_dwordx4 v9, v[96:99], s[14:15] nt
	s_add_u32 s14, s14, s19
	s_addc_u32 s15, s15, 0
	ds_read_b32 v120, v7 offset:8480
	ds_read_b32 v121, v7 offset:8612
	ds_read_b32 v122, v7 offset:8744
	ds_read_b32 v123, v7 offset:8876
	ds_read_b32 v124, v7 offset:9008
	ds_read_b32 v125, v7 offset:9140
	ds_read_b32 v126, v7 offset:9272
	ds_read_b32 v127, v7 offset:9404
	s_waitcnt lgkmcnt(0)
	v_cvt_pk_bf16_f32 v100, v120, v121
	v_cvt_pk_bf16_f32 v101, v122, v123
	v_cvt_pk_bf16_f32 v102, v124, v125
	v_cvt_pk_bf16_f32 v103, v126, v127
	global_store_dwordx4 v9, v[100:103], s[14:15] nt
	s_add_u32 s14, s14, s19
	s_addc_u32 s15, s15, 0
	ds_read_b32 v128, v7 offset:8512
	ds_read_b32 v129, v7 offset:8644
	ds_read_b32 v130, v7 offset:8776
	ds_read_b32 v131, v7 offset:8908
	ds_read_b32 v132, v7 offset:9040
	ds_read_b32 v133, v7 offset:9172
	ds_read_b32 v134, v7 offset:9304
	ds_read_b32 v135, v7 offset:9436
	s_waitcnt lgkmcnt(0)
	v_cvt_pk_bf16_f32 v104, v128, v129
	v_cvt_pk_bf16_f32 v105, v130, v131
	v_cvt_pk_bf16_f32 v106, v132, v133
	v_cvt_pk_bf16_f32 v107, v134, v135
	global_store_dwordx4 v9, v[104:107], s[14:15] nt
	s_add_u32 s14, s14, s19
	s_addc_u32 s15, s15, 0
	ds_read_b32 v136, v7 offset:8544
	ds_read_b32 v137, v7 offset:8676
	ds_read_b32 v138, v7 offset:8808
	ds_read_b32 v139, v7 offset:8940
	ds_read_b32 v140, v7 offset:9072
	ds_read_b32 v141, v7 offset:9204
	ds_read_b32 v142, v7 offset:9336
	ds_read_b32 v143, v7 offset:9468
	s_waitcnt lgkmcnt(0)
	v_cvt_pk_bf16_f32 v108, v136, v137
	v_cvt_pk_bf16_f32 v109, v138, v139
	v_cvt_pk_bf16_f32 v110, v140, v141
	v_cvt_pk_bf16_f32 v111, v142, v143
	global_store_dwordx4 v9, v[108:111], s[14:15] nt
	s_add_i32 s6, s23, s7
	s_cmpk_lt_u32 s6, 2816
	s_cbranch_scc1 .Lcvp2_item
	s_branch .Lcvp2_end

.Lcvp2_end:
	s_waitcnt vmcnt(0)
	s_waitcnt vmcnt(0)
	s_barrier
	s_mov_b64 s[0:1], exec
	v_readlane_b32 s2, v255, 5
	v_readlane_b32 s3, v255, 6
	s_and_b64 s[2:3], s[0:1], s[2:3]
	s_mov_b64 exec, s[2:3]
	s_cbranch_execz .LBB0_285
	s_add_u32 s2, s26, 0x4200
	s_addc_u32 s3, s27, 0
	s_add_i32 s4, 0, 0x24160
	v_mov_b32_e32 v1, s4
	s_waitcnt vmcnt(0) expcnt(0) lgkmcnt(0)
	ds_read_b32 v3, v1
	s_add_i32 s4, 0, 0x24164
	v_mov_b32_e32 v1, s4
	ds_read_b32 v1, v1
	s_waitcnt lgkmcnt(1)
	v_cmp_ne_u32_e32 vcc, 0, v3
	s_cbranch_vccnz .LBB0_249
	s_add_u32 s4, s26, 0x4400
	s_addc_u32 s5, s27, 0
	s_add_u32 s6, s26, 0x4500
	s_addc_u32 s7, s27, 0
	s_add_u32 s8, s26, 0x4600
	s_addc_u32 s9, s27, 0
	s_add_u32 s10, s26, 0x4700
	s_addc_u32 s11, s27, 0
	s_add_u32 s12, s26, 0x4800
	s_addc_u32 s13, s27, 0
	s_add_u32 s14, s26, 0x4900
	s_addc_u32 s15, s27, 0
	s_add_u32 s16, s26, 0x4a00
	s_addc_u32 s17, s27, 0
	s_add_u32 s18, s26, 0x4b00
	s_addc_u32 s19, s27, 0
	s_add_u32 s20, s26, 0x4c00
	s_addc_u32 s21, s27, 0
	s_add_u32 s22, s26, 0x4d00
	s_addc_u32 s23, s27, 0
	s_add_u32 s30, s26, 0x4e00
	s_addc_u32 s31, s27, 0
	s_add_u32 s34, s26, 0x4f00
	s_addc_u32 s35, s27, 0
	v_readlane_b32 s40, v255, 0
	s_add_u32 s36, s26, 0x5000
	v_readlane_b32 s41, v255, 1
	s_addc_u32 s37, s27, 0
	s_load_dwordx2 s[28:29], s[40:41], 0x4
	s_add_u32 s38, s26, 0x5100
	s_addc_u32 s39, s27, 0
	s_add_u32 s44, s26, 0x5200
	s_addc_u32 s45, s27, 0
	s_add_u32 s64, s26, 0x5300
	s_waitcnt lgkmcnt(0)
	s_mul_i32 s25, s28, s33
	s_addc_u32 s65, s27, 0
	s_mul_i32 s25, s25, s29
	s_mov_b32 s28, 1
	v_mov_b32_e32 v17, 0
	s_branch .LBB0_237

.LBB0_774:
	s_abs_i32 s0, s33
	v_cvt_f32_u32_e32 v2, s0
	s_sub_i32 s1, 0, s0
	v_rcp_iflag_f32_e32 v2, v2
	s_nop 0
	v_mul_f32_e32 v2, 0x4f7ffffe, v2
	v_cvt_u32_f32_e32 v2, v2
	s_nop 0
	v_readfirstlane_b32 s2, v2
	s_mul_i32 s1, s1, s2
	s_mul_hi_u32 s1, s2, s1
	s_add_i32 s2, s2, s1
	s_mul_hi_u32 s1, s2, 0x35a
	s_mul_i32 s1, s1, s0
	s_sub_i32 s1, 0x35a, s1
	s_sub_i32 s2, s1, s0
	s_cmp_ge_u32 s1, s0
	s_cselect_b32 s1, s2, s1
	s_sub_i32 s2, s1, s0
	s_cmp_ge_u32 s1, s0
	s_cselect_b32 s0, s2, s1
	s_movk_i32 s0, 180
	s_cmp_ge_i32 s24, s0
	s_cbranch_scc0 .LBB0_796
	s_sub_i32 s1, s24, s0
	s_lshl_b32 s1, s1, 3
	s_add_i32 s6, s1, s83
	s_cmpk_gt_u32 s6, 0x127f
	s_cbranch_scc1 .LBB0_796
	s_addk_i32 s6, 2816
	s_cmpk_gt_u32 s6, 4735
	s_cbranch_scc1 .Lcv3_end
	s_sub_i32 s7, s33, s0
	s_lshl_b32 s7, s7, 3
	v_mbcnt_lo_u32_b32 v1, -1, 0
	v_mbcnt_hi_u32_b32 v1, -1, v1
	v_and_b32_e32 v2, 31, v1
	v_lshrrev_b32_e32 v3, 5, v1
	s_mul_i32 s4, s83, 0x4400
	v_mad_u32_u24 v4, v3, 33, v2
	v_lshl_add_u32 v4, v4, 2, s4
	v_and_b32_e32 v5, 7, v1
	v_lshrrev_b32_e32 v6, 3, v1
	v_mul_u32_u24_e32 v7, 0x108, v5
	v_add_u32_e32 v7, v7, v6
	v_lshl_add_u32 v7, v7, 2, s4
